# EpiUp v3: ALIGN_EPI barrier moved inside the epilogue (leading half's load latency overlaps trailing half's last MFMA block); halo-independent blocks before the exchange barrier
# baseline (speedup 1.0000x reference)
.LBB0_246:
	v_lshlrev_b32_e32 v0, 3, v179
	v_lshl_add_u32 v0, s18, 5, v0
	s_lshl_b32 s2, s15, 6
	s_lshl_b32 s6, s76, 8
	s_add_i32 s2, s2, s6
	v_add_u32_e32 v174, s2, v177
	v_lshl_add_u32 v186, s40, 7, v0
	v_mul_u32_u24_e32 v175, 0x1600, v174
	v_lshlrev_b32_e32 v188, 2, v186
	v_lshlrev_b32_e32 v174, 2, v174
	v_lshl_add_u32 v175, v186, 1, v175
	global_load_dword v210, v174, s[86:87]
	global_load_dword v212, v174, s[86:87] offset:64
	global_load_dword v214, v174, s[86:87] offset:128
	global_load_dword v216, v174, s[86:87] offset:192
	global_load_dword v218, v174, s[86:87] offset:512
	global_load_dword v220, v174, s[86:87] offset:576
	global_load_dword v222, v174, s[86:87] offset:640
	global_load_dword v224, v174, s[86:87] offset:704
	global_load_dwordx4 v[14:17], v188, s[44:45]
	global_load_dwordx4 v[22:25], v188, s[44:45] offset:16
	global_load_dwordx4 v[26:29], v188, s[78:79]
	global_load_dwordx4 v[74:77], v188, s[78:79] offset:16
	global_load_dwordx4 v[78:81], v188, s[26:27]
	global_load_dwordx4 v[82:85], v188, s[26:27] offset:16
	s_mul_i32 s6, s76, 0x5800
	s_add_u32 s72, s46, s6
	s_addc_u32 s73, s47, 0
	s_sub_u32 s72, s72, 0x26800
	s_subb_u32 s73, s73, 0
	s_mul_i32 s6, s76, 0xb000
	s_add_u32 s76, s68, s6
	s_addc_u32 s77, s69, 0
	v_cmp_lt_i32_e64 s[40:41], 13, v177
	v_cmp_gt_i32_e64 s[42:43], 2, v177
	v_lshlrev_b32_e32 v187, 9, v177
	v_lshl_add_u32 v187, v0, 2, v187
	s_lshl_b32 s2, s15, 10
	s_add_i32 s2, s2, 0x1e400
	v_add_u32_e32 v186, s2, v187
	v_add_u32_e32 v187, 0xfffffc00, v186
	v_mul_u32_u24_e32 v176, 0x2c00, v177
	v_add_u32_e32 v176, v176, v188
	v_mul_u32_u24_e32 v178, 0x5800, v177
	v_add_u32_e32 v178, v178, v188
	v_add_u32_e32 v180, 0x2c00, v178
	s_mov_b32 s98, 0xbfb8aa3b
	s_mov_b32 s99, 0xbfb8aa3b
	s_mov_b32 s92, 1.0
	s_mov_b32 s93, 1.0
	s_waitcnt vmcnt(0)
	s_and_b64 vcc, exec, s[74:75]
	s_cbranch_vccz .Lepi_noalign
	s_barrier
.Lepi_noalign:
	v_pk_mul_f32 v[150:151], v[150:151], v[210:211] op_sel_hi:[1,0]
	v_pk_mul_f32 v[152:153], v[152:153], v[210:211] op_sel_hi:[1,0]
	v_pk_mul_f32 v[58:59], v[58:59], v[210:211] op_sel_hi:[1,0]
	v_pk_mul_f32 v[60:61], v[60:61], v[210:211] op_sel_hi:[1,0]
	v_pk_mul_f32 v[142:143], v[142:143], v[210:211] op_sel_hi:[1,0]
	v_pk_mul_f32 v[144:145], v[144:145], v[210:211] op_sel_hi:[1,0]
	v_pk_mul_f32 v[138:139], v[138:139], v[210:211] op_sel_hi:[1,0]
	v_pk_mul_f32 v[140:141], v[140:141], v[210:211] op_sel_hi:[1,0]
	v_pk_mul_f32 v[126:127], v[126:127], v[212:213] op_sel_hi:[1,0]
	v_pk_mul_f32 v[128:129], v[128:129], v[212:213] op_sel_hi:[1,0]
	v_pk_mul_f32 v[122:123], v[122:123], v[212:213] op_sel_hi:[1,0]
	v_pk_mul_f32 v[124:125], v[124:125], v[212:213] op_sel_hi:[1,0]
	v_pk_mul_f32 v[110:111], v[110:111], v[212:213] op_sel_hi:[1,0]
	v_pk_mul_f32 v[112:113], v[112:113], v[212:213] op_sel_hi:[1,0]
	v_pk_mul_f32 v[106:107], v[106:107], v[212:213] op_sel_hi:[1,0]
	v_pk_mul_f32 v[108:109], v[108:109], v[212:213] op_sel_hi:[1,0]
	v_pk_mul_f32 v[118:119], v[118:119], v[214:215] op_sel_hi:[1,0]
	v_pk_mul_f32 v[120:121], v[120:121], v[214:215] op_sel_hi:[1,0]
	v_pk_mul_f32 v[114:115], v[114:115], v[214:215] op_sel_hi:[1,0]
	v_pk_mul_f32 v[116:117], v[116:117], v[214:215] op_sel_hi:[1,0]
	v_pk_mul_f32 v[102:103], v[102:103], v[214:215] op_sel_hi:[1,0]
	v_pk_mul_f32 v[104:105], v[104:105], v[214:215] op_sel_hi:[1,0]
	v_pk_mul_f32 v[98:99], v[98:99], v[214:215] op_sel_hi:[1,0]
	v_pk_mul_f32 v[100:101], v[100:101], v[214:215] op_sel_hi:[1,0]
	v_pk_mul_f32 v[134:135], v[134:135], v[216:217] op_sel_hi:[1,0]
	v_pk_mul_f32 v[136:137], v[136:137], v[216:217] op_sel_hi:[1,0]
	v_pk_mul_f32 v[130:131], v[130:131], v[216:217] op_sel_hi:[1,0]
	v_pk_mul_f32 v[132:133], v[132:133], v[216:217] op_sel_hi:[1,0]
	v_pk_mul_f32 v[94:95], v[94:95], v[216:217] op_sel_hi:[1,0]
	v_pk_mul_f32 v[96:97], v[96:97], v[216:217] op_sel_hi:[1,0]
	v_pk_mul_f32 v[90:91], v[90:91], v[216:217] op_sel_hi:[1,0]
	v_pk_mul_f32 v[92:93], v[92:93], v[216:217] op_sel_hi:[1,0]
	v_pk_mul_f32 v[70:71], v[70:71], v[218:219] op_sel_hi:[1,0]
	v_pk_mul_f32 v[72:73], v[72:73], v[218:219] op_sel_hi:[1,0]
	v_pk_mul_f32 v[66:67], v[66:67], v[218:219] op_sel_hi:[1,0]
	v_pk_mul_f32 v[68:69], v[68:69], v[218:219] op_sel_hi:[1,0]
	v_pk_mul_f32 v[50:51], v[50:51], v[218:219] op_sel_hi:[1,0]
	v_pk_mul_f32 v[52:53], v[52:53], v[218:219] op_sel_hi:[1,0]
	v_pk_mul_f32 v[46:47], v[46:47], v[218:219] op_sel_hi:[1,0]
	v_pk_mul_f32 v[48:49], v[48:49], v[218:219] op_sel_hi:[1,0]
	v_pk_mul_f32 v[62:63], v[62:63], v[220:221] op_sel_hi:[1,0]
	v_pk_mul_f32 v[64:65], v[64:65], v[220:221] op_sel_hi:[1,0]
	v_pk_mul_f32 v[54:55], v[54:55], v[220:221] op_sel_hi:[1,0]
	v_pk_mul_f32 v[56:57], v[56:57], v[220:221] op_sel_hi:[1,0]
	v_pk_mul_f32 v[34:35], v[34:35], v[220:221] op_sel_hi:[1,0]
	v_pk_mul_f32 v[36:37], v[36:37], v[220:221] op_sel_hi:[1,0]
	v_pk_mul_f32 v[30:31], v[30:31], v[220:221] op_sel_hi:[1,0]
	v_pk_mul_f32 v[32:33], v[32:33], v[220:221] op_sel_hi:[1,0]
	v_pk_mul_f32 v[42:43], v[42:43], v[222:223] op_sel_hi:[1,0]
	v_pk_mul_f32 v[44:45], v[44:45], v[222:223] op_sel_hi:[1,0]
	v_pk_mul_f32 v[38:39], v[38:39], v[222:223] op_sel_hi:[1,0]
	v_pk_mul_f32 v[40:41], v[40:41], v[222:223] op_sel_hi:[1,0]
	v_pk_mul_f32 v[18:19], v[18:19], v[222:223] op_sel_hi:[1,0]
	v_pk_mul_f32 v[20:21], v[20:21], v[222:223] op_sel_hi:[1,0]
	v_pk_mul_f32 v[10:11], v[10:11], v[222:223] op_sel_hi:[1,0]
	v_pk_mul_f32 v[12:13], v[12:13], v[222:223] op_sel_hi:[1,0]
	v_pk_mul_f32 v[86:87], v[86:87], v[224:225] op_sel_hi:[1,0]
	v_pk_mul_f32 v[88:89], v[88:89], v[224:225] op_sel_hi:[1,0]
	v_pk_mul_f32 v[146:147], v[146:147], v[224:225] op_sel_hi:[1,0]
	v_pk_mul_f32 v[148:149], v[148:149], v[224:225] op_sel_hi:[1,0]
	v_pk_mul_f32 v[6:7], v[6:7], v[224:225] op_sel_hi:[1,0]
	v_pk_mul_f32 v[8:9], v[8:9], v[224:225] op_sel_hi:[1,0]
	v_pk_mul_f32 v[2:3], v[2:3], v[224:225] op_sel_hi:[1,0]
	v_pk_mul_f32 v[4:5], v[4:5], v[224:225] op_sel_hi:[1,0]
	s_and_saveexec_b64 s[70:71], s[40:41]
	ds_write_b128 v186, v[134:137]
	ds_write_b128 v186, v[130:133] offset:16
	ds_write_b128 v186, v[86:89] offset:2048
	ds_write_b128 v186, v[146:149] offset:2064
	s_cmp_lg_u32 s15, 1
	s_cbranch_scc1 .Lepi_nohg
	global_store_dwordx4 v176, v[86:89], s[72:73]
	global_store_dwordx4 v176, v[146:149], s[72:73] offset:16

.Lepi_nohr:
	v_cmp_eq_u32_e32 vcc, 0, v177
	v_cndmask_b32_e64 v182, 0, v14, s[42:43]
	v_cndmask_b32_e64 v183, 0, v15, s[42:43]
	v_cndmask_b32_e64 v184, 0, v16, s[42:43]
	v_cndmask_b32_e64 v185, 0, v17, s[42:43]
	v_cndmask_b32_e64 v190, 0, v22, s[42:43]
	v_cndmask_b32_e64 v191, 0, v23, s[42:43]
	v_cndmask_b32_e64 v192, 0, v24, s[42:43]
	v_cndmask_b32_e64 v193, 0, v25, s[42:43]
	v_cndmask_b32_e32 v154, 0, v26, vcc
	v_cndmask_b32_e32 v155, 0, v27, vcc
	v_cndmask_b32_e32 v156, 0, v28, vcc
	v_cndmask_b32_e32 v157, 0, v29, vcc
	v_cndmask_b32_e32 v158, 0, v74, vcc
	v_cndmask_b32_e32 v159, 0, v75, vcc
	v_cndmask_b32_e32 v160, 0, v76, vcc
	v_cndmask_b32_e32 v161, 0, v77, vcc
	v_pk_mul_f32 v[202:203], v[126:127], v[78:79]
	v_pk_mul_f32 v[204:205], v[128:129], v[80:81]
	v_pk_mul_f32 v[206:207], v[122:123], v[82:83]
	v_pk_mul_f32 v[226:227], v[124:125], v[84:85]
	v_fmac_f32_dpp v202, v126, v26 row_shr:1 row_mask:0xf bank_mask:0xf bound_ctrl:1
	v_fmac_f32_dpp v203, v127, v27 row_shr:1 row_mask:0xf bank_mask:0xf bound_ctrl:1
	v_fmac_f32_dpp v204, v128, v28 row_shr:1 row_mask:0xf bank_mask:0xf bound_ctrl:1
	v_fmac_f32_dpp v205, v129, v29 row_shr:1 row_mask:0xf bank_mask:0xf bound_ctrl:1
	v_fmac_f32_dpp v206, v122, v74 row_shr:1 row_mask:0xf bank_mask:0xf bound_ctrl:1
	v_fmac_f32_dpp v207, v123, v75 row_shr:1 row_mask:0xf bank_mask:0xf bound_ctrl:1
	v_fmac_f32_dpp v226, v124, v76 row_shr:1 row_mask:0xf bank_mask:0xf bound_ctrl:1
	v_fmac_f32_dpp v227, v125, v77 row_shr:1 row_mask:0xf bank_mask:0xf bound_ctrl:1
	v_fmac_f32_dpp v202, v126, v14 row_shr:2 row_mask:0xf bank_mask:0xf bound_ctrl:1
	v_fmac_f32_dpp v203, v127, v15 row_shr:2 row_mask:0xf bank_mask:0xf bound_ctrl:1
	v_fmac_f32_dpp v204, v128, v16 row_shr:2 row_mask:0xf bank_mask:0xf bound_ctrl:1
	v_fmac_f32_dpp v205, v129, v17 row_shr:2 row_mask:0xf bank_mask:0xf bound_ctrl:1
	v_fmac_f32_dpp v206, v122, v22 row_shr:2 row_mask:0xf bank_mask:0xf bound_ctrl:1
	v_fmac_f32_dpp v207, v123, v23 row_shr:2 row_mask:0xf bank_mask:0xf bound_ctrl:1
	v_fmac_f32_dpp v226, v124, v24 row_shr:2 row_mask:0xf bank_mask:0xf bound_ctrl:1
	v_fmac_f32_dpp v227, v125, v25 row_shr:2 row_mask:0xf bank_mask:0xf bound_ctrl:1
	v_fmac_f32_dpp v202, v150, v154 row_ror:1 row_mask:0xf bank_mask:0xf bound_ctrl:1
	v_fmac_f32_dpp v203, v151, v155 row_ror:1 row_mask:0xf bank_mask:0xf bound_ctrl:1
	v_fmac_f32_dpp v204, v152, v156 row_ror:1 row_mask:0xf bank_mask:0xf bound_ctrl:1
	v_fmac_f32_dpp v205, v153, v157 row_ror:1 row_mask:0xf bank_mask:0xf bound_ctrl:1
	v_fmac_f32_dpp v206, v58, v158 row_ror:1 row_mask:0xf bank_mask:0xf bound_ctrl:1
	v_fmac_f32_dpp v207, v59, v159 row_ror:1 row_mask:0xf bank_mask:0xf bound_ctrl:1
	v_fmac_f32_dpp v226, v60, v160 row_ror:1 row_mask:0xf bank_mask:0xf bound_ctrl:1
	v_fmac_f32_dpp v227, v61, v161 row_ror:1 row_mask:0xf bank_mask:0xf bound_ctrl:1
	v_fmac_f32_dpp v202, v150, v182 row_ror:2 row_mask:0xf bank_mask:0xf bound_ctrl:1
	v_fmac_f32_dpp v203, v151, v183 row_ror:2 row_mask:0xf bank_mask:0xf bound_ctrl:1
	v_fmac_f32_dpp v204, v152, v184 row_ror:2 row_mask:0xf bank_mask:0xf bound_ctrl:1
	v_fmac_f32_dpp v205, v153, v185 row_ror:2 row_mask:0xf bank_mask:0xf bound_ctrl:1
	v_fmac_f32_dpp v206, v58, v190 row_ror:2 row_mask:0xf bank_mask:0xf bound_ctrl:1
	v_fmac_f32_dpp v207, v59, v191 row_ror:2 row_mask:0xf bank_mask:0xf bound_ctrl:1
	v_fmac_f32_dpp v226, v60, v192 row_ror:2 row_mask:0xf bank_mask:0xf bound_ctrl:1
	v_fmac_f32_dpp v227, v61, v193 row_ror:2 row_mask:0xf bank_mask:0xf bound_ctrl:1
	s_add_u32 s72, s84, 0x16000
	v_pk_mul_f32 v[218:219], v[118:119], v[78:79]
	s_addc_u32 s73, s85, 0
	v_pk_mul_f32 v[220:221], v[120:121], v[80:81]
	v_pk_mul_f32 v[242:243], v[202:203], s[98:99]
	v_pk_mul_f32 v[222:223], v[114:115], v[82:83]
	v_pk_mul_f32 v[244:245], v[204:205], s[98:99]
	v_pk_mul_f32 v[224:225], v[116:117], v[84:85]
	v_pk_mul_f32 v[246:247], v[206:207], s[98:99]
	v_fmac_f32_dpp v218, v118, v26 row_shr:1 row_mask:0xf bank_mask:0xf bound_ctrl:1
	v_pk_mul_f32 v[248:249], v[226:227], s[98:99]
	v_fmac_f32_dpp v219, v119, v27 row_shr:1 row_mask:0xf bank_mask:0xf bound_ctrl:1
	v_exp_f32_e32 v242, v242
	v_fmac_f32_dpp v220, v120, v28 row_shr:1 row_mask:0xf bank_mask:0xf bound_ctrl:1
	v_exp_f32_e32 v243, v243
	v_fmac_f32_dpp v221, v121, v29 row_shr:1 row_mask:0xf bank_mask:0xf bound_ctrl:1
	v_exp_f32_e32 v244, v244
	v_fmac_f32_dpp v222, v114, v74 row_shr:1 row_mask:0xf bank_mask:0xf bound_ctrl:1
	v_exp_f32_e32 v245, v245
	v_fmac_f32_dpp v223, v115, v75 row_shr:1 row_mask:0xf bank_mask:0xf bound_ctrl:1
	v_exp_f32_e32 v246, v246
	v_fmac_f32_dpp v224, v116, v76 row_shr:1 row_mask:0xf bank_mask:0xf bound_ctrl:1
	v_exp_f32_e32 v247, v247
	v_fmac_f32_dpp v225, v117, v77 row_shr:1 row_mask:0xf bank_mask:0xf bound_ctrl:1
	v_exp_f32_e32 v248, v248
	v_fmac_f32_dpp v218, v118, v14 row_shr:2 row_mask:0xf bank_mask:0xf bound_ctrl:1
	v_exp_f32_e32 v249, v249
	v_fmac_f32_dpp v219, v119, v15 row_shr:2 row_mask:0xf bank_mask:0xf bound_ctrl:1
	v_pk_add_f32 v[242:243], v[242:243], s[92:93]
	v_fmac_f32_dpp v220, v120, v16 row_shr:2 row_mask:0xf bank_mask:0xf bound_ctrl:1
	v_pk_add_f32 v[244:245], v[244:245], s[92:93]
	v_fmac_f32_dpp v221, v121, v17 row_shr:2 row_mask:0xf bank_mask:0xf bound_ctrl:1
	v_pk_add_f32 v[246:247], v[246:247], s[92:93]
	v_fmac_f32_dpp v222, v114, v22 row_shr:2 row_mask:0xf bank_mask:0xf bound_ctrl:1
	v_pk_add_f32 v[248:249], v[248:249], s[92:93]
	v_fmac_f32_dpp v223, v115, v23 row_shr:2 row_mask:0xf bank_mask:0xf bound_ctrl:1
	v_rcp_f32_e32 v242, v242
	v_fmac_f32_dpp v224, v116, v24 row_shr:2 row_mask:0xf bank_mask:0xf bound_ctrl:1
	v_rcp_f32_e32 v243, v243
	v_fmac_f32_dpp v225, v117, v25 row_shr:2 row_mask:0xf bank_mask:0xf bound_ctrl:1
	v_rcp_f32_e32 v244, v244
	v_fmac_f32_dpp v218, v126, v154 row_ror:1 row_mask:0xf bank_mask:0xf bound_ctrl:1
	v_rcp_f32_e32 v245, v245
	v_fmac_f32_dpp v219, v127, v155 row_ror:1 row_mask:0xf bank_mask:0xf bound_ctrl:1
	v_rcp_f32_e32 v246, v246
	v_fmac_f32_dpp v220, v128, v156 row_ror:1 row_mask:0xf bank_mask:0xf bound_ctrl:1
	v_rcp_f32_e32 v247, v247
	v_fmac_f32_dpp v221, v129, v157 row_ror:1 row_mask:0xf bank_mask:0xf bound_ctrl:1
	v_rcp_f32_e32 v248, v248
	v_fmac_f32_dpp v222, v122, v158 row_ror:1 row_mask:0xf bank_mask:0xf bound_ctrl:1
	v_rcp_f32_e32 v249, v249
	v_fmac_f32_dpp v223, v123, v159 row_ror:1 row_mask:0xf bank_mask:0xf bound_ctrl:1
	v_pk_mul_f32 v[202:203], v[202:203], v[242:243]
	v_fmac_f32_dpp v224, v124, v160 row_ror:1 row_mask:0xf bank_mask:0xf bound_ctrl:1
	v_pk_mul_f32 v[204:205], v[204:205], v[244:245]
	v_fmac_f32_dpp v225, v125, v161 row_ror:1 row_mask:0xf bank_mask:0xf bound_ctrl:1
	v_pk_mul_f32 v[206:207], v[206:207], v[246:247]
	v_fmac_f32_dpp v218, v126, v182 row_ror:2 row_mask:0xf bank_mask:0xf bound_ctrl:1
	v_pk_mul_f32 v[226:227], v[226:227], v[248:249]
	v_fmac_f32_dpp v219, v127, v183 row_ror:2 row_mask:0xf bank_mask:0xf bound_ctrl:1
	v_pk_mul_f32 v[110:111], v[110:111], v[202:203]
	v_fmac_f32_dpp v220, v128, v184 row_ror:2 row_mask:0xf bank_mask:0xf bound_ctrl:1
	v_pk_mul_f32 v[112:113], v[112:113], v[204:205]
	v_fmac_f32_dpp v221, v129, v185 row_ror:2 row_mask:0xf bank_mask:0xf bound_ctrl:1
	v_pk_mul_f32 v[106:107], v[106:107], v[206:207]
	v_fmac_f32_dpp v222, v122, v190 row_ror:2 row_mask:0xf bank_mask:0xf bound_ctrl:1
	v_pk_mul_f32 v[108:109], v[108:109], v[226:227]
	v_fmac_f32_dpp v223, v123, v191 row_ror:2 row_mask:0xf bank_mask:0xf bound_ctrl:1
	v_cvt_pk_bf16_f32 v250, v110, v111
	v_fmac_f32_dpp v224, v124, v192 row_ror:2 row_mask:0xf bank_mask:0xf bound_ctrl:1
	v_cvt_pk_bf16_f32 v251, v112, v113
	v_fmac_f32_dpp v225, v125, v193 row_ror:2 row_mask:0xf bank_mask:0xf bound_ctrl:1
	v_cvt_pk_bf16_f32 v252, v106, v107
	v_cvt_pk_bf16_f32 v253, v108, v109
	global_store_dwordx4 v175, v[250:253], s[72:73]
	s_add_u32 s72, s84, 0x2c000
	v_pk_mul_f32 v[202:203], v[134:135], v[78:79]
	s_addc_u32 s73, s85, 0
	v_pk_mul_f32 v[204:205], v[136:137], v[80:81]
	v_pk_mul_f32 v[242:243], v[218:219], s[98:99]
	v_pk_mul_f32 v[206:207], v[130:131], v[82:83]
	v_pk_mul_f32 v[244:245], v[220:221], s[98:99]
	v_pk_mul_f32 v[226:227], v[132:133], v[84:85]
	v_pk_mul_f32 v[246:247], v[222:223], s[98:99]
	v_fmac_f32_dpp v202, v134, v26 row_shr:1 row_mask:0xf bank_mask:0xf bound_ctrl:1
	v_pk_mul_f32 v[248:249], v[224:225], s[98:99]
	v_fmac_f32_dpp v203, v135, v27 row_shr:1 row_mask:0xf bank_mask:0xf bound_ctrl:1
	v_exp_f32_e32 v242, v242
	v_fmac_f32_dpp v204, v136, v28 row_shr:1 row_mask:0xf bank_mask:0xf bound_ctrl:1
	v_exp_f32_e32 v243, v243
	v_fmac_f32_dpp v205, v137, v29 row_shr:1 row_mask:0xf bank_mask:0xf bound_ctrl:1
	v_exp_f32_e32 v244, v244
	v_fmac_f32_dpp v206, v130, v74 row_shr:1 row_mask:0xf bank_mask:0xf bound_ctrl:1
	v_exp_f32_e32 v245, v245
	v_fmac_f32_dpp v207, v131, v75 row_shr:1 row_mask:0xf bank_mask:0xf bound_ctrl:1
	v_exp_f32_e32 v246, v246
	v_fmac_f32_dpp v226, v132, v76 row_shr:1 row_mask:0xf bank_mask:0xf bound_ctrl:1
	v_exp_f32_e32 v247, v247
	v_fmac_f32_dpp v227, v133, v77 row_shr:1 row_mask:0xf bank_mask:0xf bound_ctrl:1
	v_exp_f32_e32 v248, v248
	v_fmac_f32_dpp v202, v134, v14 row_shr:2 row_mask:0xf bank_mask:0xf bound_ctrl:1
	v_exp_f32_e32 v249, v249
	v_fmac_f32_dpp v203, v135, v15 row_shr:2 row_mask:0xf bank_mask:0xf bound_ctrl:1
	v_pk_add_f32 v[242:243], v[242:243], s[92:93]
	v_fmac_f32_dpp v204, v136, v16 row_shr:2 row_mask:0xf bank_mask:0xf bound_ctrl:1
	v_pk_add_f32 v[244:245], v[244:245], s[92:93]
	v_fmac_f32_dpp v205, v137, v17 row_shr:2 row_mask:0xf bank_mask:0xf bound_ctrl:1
	v_pk_add_f32 v[246:247], v[246:247], s[92:93]
	v_fmac_f32_dpp v206, v130, v22 row_shr:2 row_mask:0xf bank_mask:0xf bound_ctrl:1
	v_pk_add_f32 v[248:249], v[248:249], s[92:93]
	v_fmac_f32_dpp v207, v131, v23 row_shr:2 row_mask:0xf bank_mask:0xf bound_ctrl:1
	v_rcp_f32_e32 v242, v242
	v_fmac_f32_dpp v226, v132, v24 row_shr:2 row_mask:0xf bank_mask:0xf bound_ctrl:1
	v_rcp_f32_e32 v243, v243
	v_fmac_f32_dpp v227, v133, v25 row_shr:2 row_mask:0xf bank_mask:0xf bound_ctrl:1
	v_rcp_f32_e32 v244, v244
	v_fmac_f32_dpp v202, v118, v154 row_ror:1 row_mask:0xf bank_mask:0xf bound_ctrl:1
	v_rcp_f32_e32 v245, v245
	v_fmac_f32_dpp v203, v119, v155 row_ror:1 row_mask:0xf bank_mask:0xf bound_ctrl:1
	v_rcp_f32_e32 v246, v246
	v_fmac_f32_dpp v204, v120, v156 row_ror:1 row_mask:0xf bank_mask:0xf bound_ctrl:1
	v_rcp_f32_e32 v247, v247
	v_fmac_f32_dpp v205, v121, v157 row_ror:1 row_mask:0xf bank_mask:0xf bound_ctrl:1
	v_rcp_f32_e32 v248, v248
	v_fmac_f32_dpp v206, v114, v158 row_ror:1 row_mask:0xf bank_mask:0xf bound_ctrl:1
	v_rcp_f32_e32 v249, v249
	v_fmac_f32_dpp v207, v115, v159 row_ror:1 row_mask:0xf bank_mask:0xf bound_ctrl:1
	v_pk_mul_f32 v[218:219], v[218:219], v[242:243]
	v_fmac_f32_dpp v226, v116, v160 row_ror:1 row_mask:0xf bank_mask:0xf bound_ctrl:1
	v_pk_mul_f32 v[220:221], v[220:221], v[244:245]
	v_fmac_f32_dpp v227, v117, v161 row_ror:1 row_mask:0xf bank_mask:0xf bound_ctrl:1
	v_pk_mul_f32 v[222:223], v[222:223], v[246:247]
	v_fmac_f32_dpp v202, v118, v182 row_ror:2 row_mask:0xf bank_mask:0xf bound_ctrl:1
	v_pk_mul_f32 v[224:225], v[224:225], v[248:249]
	v_fmac_f32_dpp v203, v119, v183 row_ror:2 row_mask:0xf bank_mask:0xf bound_ctrl:1
	v_pk_mul_f32 v[102:103], v[102:103], v[218:219]
	v_fmac_f32_dpp v204, v120, v184 row_ror:2 row_mask:0xf bank_mask:0xf bound_ctrl:1
	v_pk_mul_f32 v[104:105], v[104:105], v[220:221]
	v_fmac_f32_dpp v205, v121, v185 row_ror:2 row_mask:0xf bank_mask:0xf bound_ctrl:1
	v_pk_mul_f32 v[98:99], v[98:99], v[222:223]
	v_fmac_f32_dpp v206, v114, v190 row_ror:2 row_mask:0xf bank_mask:0xf bound_ctrl:1
	v_pk_mul_f32 v[100:101], v[100:101], v[224:225]
	v_fmac_f32_dpp v207, v115, v191 row_ror:2 row_mask:0xf bank_mask:0xf bound_ctrl:1
	v_cvt_pk_bf16_f32 v250, v102, v103
	v_fmac_f32_dpp v226, v116, v192 row_ror:2 row_mask:0xf bank_mask:0xf bound_ctrl:1
	v_cvt_pk_bf16_f32 v251, v104, v105
	v_fmac_f32_dpp v227, v117, v193 row_ror:2 row_mask:0xf bank_mask:0xf bound_ctrl:1
	v_cvt_pk_bf16_f32 v252, v98, v99
	v_cvt_pk_bf16_f32 v253, v100, v101
	global_store_dwordx4 v175, v[250:253], s[72:73]
	s_add_u32 s72, s84, 0x42000
	v_pk_mul_f32 v[218:219], v[62:63], v[78:79]
	s_addc_u32 s73, s85, 0
	v_pk_mul_f32 v[220:221], v[64:65], v[80:81]
	v_pk_mul_f32 v[242:243], v[202:203], s[98:99]
	v_pk_mul_f32 v[222:223], v[54:55], v[82:83]
	v_pk_mul_f32 v[244:245], v[204:205], s[98:99]
	v_pk_mul_f32 v[224:225], v[56:57], v[84:85]
	v_pk_mul_f32 v[246:247], v[206:207], s[98:99]
	v_fmac_f32_dpp v218, v62, v26 row_shr:1 row_mask:0xf bank_mask:0xf bound_ctrl:1
	v_pk_mul_f32 v[248:249], v[226:227], s[98:99]
	v_fmac_f32_dpp v219, v63, v27 row_shr:1 row_mask:0xf bank_mask:0xf bound_ctrl:1
	v_exp_f32_e32 v242, v242
	v_fmac_f32_dpp v220, v64, v28 row_shr:1 row_mask:0xf bank_mask:0xf bound_ctrl:1
	v_exp_f32_e32 v243, v243
	v_fmac_f32_dpp v221, v65, v29 row_shr:1 row_mask:0xf bank_mask:0xf bound_ctrl:1
	v_exp_f32_e32 v244, v244
	v_fmac_f32_dpp v222, v54, v74 row_shr:1 row_mask:0xf bank_mask:0xf bound_ctrl:1
	v_exp_f32_e32 v245, v245
	v_fmac_f32_dpp v223, v55, v75 row_shr:1 row_mask:0xf bank_mask:0xf bound_ctrl:1
	v_exp_f32_e32 v246, v246
	v_fmac_f32_dpp v224, v56, v76 row_shr:1 row_mask:0xf bank_mask:0xf bound_ctrl:1
	v_exp_f32_e32 v247, v247
	v_fmac_f32_dpp v225, v57, v77 row_shr:1 row_mask:0xf bank_mask:0xf bound_ctrl:1
	v_exp_f32_e32 v248, v248
	v_fmac_f32_dpp v218, v62, v14 row_shr:2 row_mask:0xf bank_mask:0xf bound_ctrl:1
	v_exp_f32_e32 v249, v249
	v_fmac_f32_dpp v219, v63, v15 row_shr:2 row_mask:0xf bank_mask:0xf bound_ctrl:1
	v_pk_add_f32 v[242:243], v[242:243], s[92:93]
	v_fmac_f32_dpp v220, v64, v16 row_shr:2 row_mask:0xf bank_mask:0xf bound_ctrl:1
	v_pk_add_f32 v[244:245], v[244:245], s[92:93]
	v_fmac_f32_dpp v221, v65, v17 row_shr:2 row_mask:0xf bank_mask:0xf bound_ctrl:1
	v_pk_add_f32 v[246:247], v[246:247], s[92:93]
	v_fmac_f32_dpp v222, v54, v22 row_shr:2 row_mask:0xf bank_mask:0xf bound_ctrl:1
	v_pk_add_f32 v[248:249], v[248:249], s[92:93]
	v_fmac_f32_dpp v223, v55, v23 row_shr:2 row_mask:0xf bank_mask:0xf bound_ctrl:1
	v_rcp_f32_e32 v242, v242
	v_fmac_f32_dpp v224, v56, v24 row_shr:2 row_mask:0xf bank_mask:0xf bound_ctrl:1
	v_rcp_f32_e32 v243, v243
	v_fmac_f32_dpp v225, v57, v25 row_shr:2 row_mask:0xf bank_mask:0xf bound_ctrl:1
	v_rcp_f32_e32 v244, v244
	v_fmac_f32_dpp v218, v70, v154 row_ror:1 row_mask:0xf bank_mask:0xf bound_ctrl:1
	v_rcp_f32_e32 v245, v245
	v_fmac_f32_dpp v219, v71, v155 row_ror:1 row_mask:0xf bank_mask:0xf bound_ctrl:1
	v_rcp_f32_e32 v246, v246
	v_fmac_f32_dpp v220, v72, v156 row_ror:1 row_mask:0xf bank_mask:0xf bound_ctrl:1
	v_rcp_f32_e32 v247, v247
	v_fmac_f32_dpp v221, v73, v157 row_ror:1 row_mask:0xf bank_mask:0xf bound_ctrl:1
	v_rcp_f32_e32 v248, v248
	v_fmac_f32_dpp v222, v66, v158 row_ror:1 row_mask:0xf bank_mask:0xf bound_ctrl:1
	v_rcp_f32_e32 v249, v249
	v_fmac_f32_dpp v223, v67, v159 row_ror:1 row_mask:0xf bank_mask:0xf bound_ctrl:1
	v_pk_mul_f32 v[202:203], v[202:203], v[242:243]
	v_fmac_f32_dpp v224, v68, v160 row_ror:1 row_mask:0xf bank_mask:0xf bound_ctrl:1
	v_pk_mul_f32 v[204:205], v[204:205], v[244:245]
	v_fmac_f32_dpp v225, v69, v161 row_ror:1 row_mask:0xf bank_mask:0xf bound_ctrl:1
	v_pk_mul_f32 v[206:207], v[206:207], v[246:247]
	v_fmac_f32_dpp v218, v70, v182 row_ror:2 row_mask:0xf bank_mask:0xf bound_ctrl:1
	v_pk_mul_f32 v[226:227], v[226:227], v[248:249]
	v_fmac_f32_dpp v219, v71, v183 row_ror:2 row_mask:0xf bank_mask:0xf bound_ctrl:1
	v_pk_mul_f32 v[94:95], v[94:95], v[202:203]
	v_fmac_f32_dpp v220, v72, v184 row_ror:2 row_mask:0xf bank_mask:0xf bound_ctrl:1
	v_pk_mul_f32 v[96:97], v[96:97], v[204:205]
	v_fmac_f32_dpp v221, v73, v185 row_ror:2 row_mask:0xf bank_mask:0xf bound_ctrl:1
	v_pk_mul_f32 v[90:91], v[90:91], v[206:207]
	v_fmac_f32_dpp v222, v66, v190 row_ror:2 row_mask:0xf bank_mask:0xf bound_ctrl:1
	v_pk_mul_f32 v[92:93], v[92:93], v[226:227]
	v_fmac_f32_dpp v223, v67, v191 row_ror:2 row_mask:0xf bank_mask:0xf bound_ctrl:1
	v_cvt_pk_bf16_f32 v250, v94, v95
	v_fmac_f32_dpp v224, v68, v192 row_ror:2 row_mask:0xf bank_mask:0xf bound_ctrl:1
	v_cvt_pk_bf16_f32 v251, v96, v97
	v_fmac_f32_dpp v225, v69, v193 row_ror:2 row_mask:0xf bank_mask:0xf bound_ctrl:1
	v_cvt_pk_bf16_f32 v252, v90, v91
	v_cvt_pk_bf16_f32 v253, v92, v93
	global_store_dwordx4 v175, v[250:253], s[72:73]
	s_add_u32 s72, s84, 0xc6000
	v_pk_mul_f32 v[202:203], v[42:43], v[78:79]
	s_addc_u32 s73, s85, 0
	v_pk_mul_f32 v[204:205], v[44:45], v[80:81]
	v_pk_mul_f32 v[242:243], v[218:219], s[98:99]
	v_pk_mul_f32 v[206:207], v[38:39], v[82:83]
	v_pk_mul_f32 v[244:245], v[220:221], s[98:99]
	v_pk_mul_f32 v[226:227], v[40:41], v[84:85]
	v_pk_mul_f32 v[246:247], v[222:223], s[98:99]
	v_fmac_f32_dpp v202, v42, v26 row_shr:1 row_mask:0xf bank_mask:0xf bound_ctrl:1
	v_pk_mul_f32 v[248:249], v[224:225], s[98:99]
	v_fmac_f32_dpp v203, v43, v27 row_shr:1 row_mask:0xf bank_mask:0xf bound_ctrl:1
	v_exp_f32_e32 v242, v242
	v_fmac_f32_dpp v204, v44, v28 row_shr:1 row_mask:0xf bank_mask:0xf bound_ctrl:1
	v_exp_f32_e32 v243, v243
	v_fmac_f32_dpp v205, v45, v29 row_shr:1 row_mask:0xf bank_mask:0xf bound_ctrl:1
	v_exp_f32_e32 v244, v244
	v_fmac_f32_dpp v206, v38, v74 row_shr:1 row_mask:0xf bank_mask:0xf bound_ctrl:1
	v_exp_f32_e32 v245, v245
	v_fmac_f32_dpp v207, v39, v75 row_shr:1 row_mask:0xf bank_mask:0xf bound_ctrl:1
	v_exp_f32_e32 v246, v246
	v_fmac_f32_dpp v226, v40, v76 row_shr:1 row_mask:0xf bank_mask:0xf bound_ctrl:1
	v_exp_f32_e32 v247, v247
	v_fmac_f32_dpp v227, v41, v77 row_shr:1 row_mask:0xf bank_mask:0xf bound_ctrl:1
	v_exp_f32_e32 v248, v248
	v_fmac_f32_dpp v202, v42, v14 row_shr:2 row_mask:0xf bank_mask:0xf bound_ctrl:1
	v_exp_f32_e32 v249, v249
	v_fmac_f32_dpp v203, v43, v15 row_shr:2 row_mask:0xf bank_mask:0xf bound_ctrl:1
	v_pk_add_f32 v[242:243], v[242:243], s[92:93]
	v_fmac_f32_dpp v204, v44, v16 row_shr:2 row_mask:0xf bank_mask:0xf bound_ctrl:1
	v_pk_add_f32 v[244:245], v[244:245], s[92:93]
	v_fmac_f32_dpp v205, v45, v17 row_shr:2 row_mask:0xf bank_mask:0xf bound_ctrl:1
	v_pk_add_f32 v[246:247], v[246:247], s[92:93]
	v_fmac_f32_dpp v206, v38, v22 row_shr:2 row_mask:0xf bank_mask:0xf bound_ctrl:1
	v_pk_add_f32 v[248:249], v[248:249], s[92:93]
	v_fmac_f32_dpp v207, v39, v23 row_shr:2 row_mask:0xf bank_mask:0xf bound_ctrl:1
	v_rcp_f32_e32 v242, v242
	v_fmac_f32_dpp v226, v40, v24 row_shr:2 row_mask:0xf bank_mask:0xf bound_ctrl:1
	v_rcp_f32_e32 v243, v243
	v_fmac_f32_dpp v227, v41, v25 row_shr:2 row_mask:0xf bank_mask:0xf bound_ctrl:1
	v_rcp_f32_e32 v244, v244
	v_fmac_f32_dpp v202, v62, v154 row_ror:1 row_mask:0xf bank_mask:0xf bound_ctrl:1
	v_rcp_f32_e32 v245, v245
	v_fmac_f32_dpp v203, v63, v155 row_ror:1 row_mask:0xf bank_mask:0xf bound_ctrl:1
	v_rcp_f32_e32 v246, v246
	v_fmac_f32_dpp v204, v64, v156 row_ror:1 row_mask:0xf bank_mask:0xf bound_ctrl:1
	v_rcp_f32_e32 v247, v247
	v_fmac_f32_dpp v205, v65, v157 row_ror:1 row_mask:0xf bank_mask:0xf bound_ctrl:1
	v_rcp_f32_e32 v248, v248
	v_fmac_f32_dpp v206, v54, v158 row_ror:1 row_mask:0xf bank_mask:0xf bound_ctrl:1
	v_rcp_f32_e32 v249, v249
	v_fmac_f32_dpp v207, v55, v159 row_ror:1 row_mask:0xf bank_mask:0xf bound_ctrl:1
	v_pk_mul_f32 v[218:219], v[218:219], v[242:243]
	v_fmac_f32_dpp v226, v56, v160 row_ror:1 row_mask:0xf bank_mask:0xf bound_ctrl:1
	v_pk_mul_f32 v[220:221], v[220:221], v[244:245]
	v_fmac_f32_dpp v227, v57, v161 row_ror:1 row_mask:0xf bank_mask:0xf bound_ctrl:1
	v_pk_mul_f32 v[222:223], v[222:223], v[246:247]
	v_fmac_f32_dpp v202, v62, v182 row_ror:2 row_mask:0xf bank_mask:0xf bound_ctrl:1
	v_pk_mul_f32 v[224:225], v[224:225], v[248:249]
	v_fmac_f32_dpp v203, v63, v183 row_ror:2 row_mask:0xf bank_mask:0xf bound_ctrl:1
	v_pk_mul_f32 v[34:35], v[34:35], v[218:219]
	v_fmac_f32_dpp v204, v64, v184 row_ror:2 row_mask:0xf bank_mask:0xf bound_ctrl:1
	v_pk_mul_f32 v[36:37], v[36:37], v[220:221]
	v_fmac_f32_dpp v205, v65, v185 row_ror:2 row_mask:0xf bank_mask:0xf bound_ctrl:1
	v_pk_mul_f32 v[30:31], v[30:31], v[222:223]
	v_fmac_f32_dpp v206, v54, v190 row_ror:2 row_mask:0xf bank_mask:0xf bound_ctrl:1
	v_pk_mul_f32 v[32:33], v[32:33], v[224:225]
	v_fmac_f32_dpp v207, v55, v191 row_ror:2 row_mask:0xf bank_mask:0xf bound_ctrl:1
	v_cvt_pk_bf16_f32 v250, v34, v35
	v_fmac_f32_dpp v226, v56, v192 row_ror:2 row_mask:0xf bank_mask:0xf bound_ctrl:1
	v_cvt_pk_bf16_f32 v251, v36, v37
	v_fmac_f32_dpp v227, v57, v193 row_ror:2 row_mask:0xf bank_mask:0xf bound_ctrl:1
	v_cvt_pk_bf16_f32 v252, v30, v31
	v_cvt_pk_bf16_f32 v253, v32, v33
	global_store_dwordx4 v175, v[250:253], s[72:73]
	s_add_u32 s72, s84, 0xdc000
	v_pk_mul_f32 v[218:219], v[86:87], v[78:79]
	s_addc_u32 s73, s85, 0
	v_pk_mul_f32 v[220:221], v[88:89], v[80:81]
	v_pk_mul_f32 v[242:243], v[202:203], s[98:99]
	v_pk_mul_f32 v[222:223], v[146:147], v[82:83]
	v_pk_mul_f32 v[244:245], v[204:205], s[98:99]
	v_pk_mul_f32 v[224:225], v[148:149], v[84:85]
	v_pk_mul_f32 v[246:247], v[206:207], s[98:99]
	v_fmac_f32_dpp v218, v86, v26 row_shr:1 row_mask:0xf bank_mask:0xf bound_ctrl:1
	v_pk_mul_f32 v[248:249], v[226:227], s[98:99]
	v_fmac_f32_dpp v219, v87, v27 row_shr:1 row_mask:0xf bank_mask:0xf bound_ctrl:1
	v_exp_f32_e32 v242, v242
	v_fmac_f32_dpp v220, v88, v28 row_shr:1 row_mask:0xf bank_mask:0xf bound_ctrl:1
	v_exp_f32_e32 v243, v243
	v_fmac_f32_dpp v221, v89, v29 row_shr:1 row_mask:0xf bank_mask:0xf bound_ctrl:1
	v_exp_f32_e32 v244, v244
	v_fmac_f32_dpp v222, v146, v74 row_shr:1 row_mask:0xf bank_mask:0xf bound_ctrl:1
	v_exp_f32_e32 v245, v245
	v_fmac_f32_dpp v223, v147, v75 row_shr:1 row_mask:0xf bank_mask:0xf bound_ctrl:1
	v_exp_f32_e32 v246, v246
	v_fmac_f32_dpp v224, v148, v76 row_shr:1 row_mask:0xf bank_mask:0xf bound_ctrl:1
	v_exp_f32_e32 v247, v247
	v_fmac_f32_dpp v225, v149, v77 row_shr:1 row_mask:0xf bank_mask:0xf bound_ctrl:1
	v_exp_f32_e32 v248, v248
	v_fmac_f32_dpp v218, v86, v14 row_shr:2 row_mask:0xf bank_mask:0xf bound_ctrl:1
	v_exp_f32_e32 v249, v249
	v_fmac_f32_dpp v219, v87, v15 row_shr:2 row_mask:0xf bank_mask:0xf bound_ctrl:1
	v_pk_add_f32 v[242:243], v[242:243], s[92:93]
	v_fmac_f32_dpp v220, v88, v16 row_shr:2 row_mask:0xf bank_mask:0xf bound_ctrl:1
	v_pk_add_f32 v[244:245], v[244:245], s[92:93]
	v_fmac_f32_dpp v221, v89, v17 row_shr:2 row_mask:0xf bank_mask:0xf bound_ctrl:1
	v_pk_add_f32 v[246:247], v[246:247], s[92:93]
	v_fmac_f32_dpp v222, v146, v22 row_shr:2 row_mask:0xf bank_mask:0xf bound_ctrl:1
	v_pk_add_f32 v[248:249], v[248:249], s[92:93]
	v_fmac_f32_dpp v223, v147, v23 row_shr:2 row_mask:0xf bank_mask:0xf bound_ctrl:1
	v_rcp_f32_e32 v242, v242
	v_fmac_f32_dpp v224, v148, v24 row_shr:2 row_mask:0xf bank_mask:0xf bound_ctrl:1
	v_rcp_f32_e32 v243, v243
	v_fmac_f32_dpp v225, v149, v25 row_shr:2 row_mask:0xf bank_mask:0xf bound_ctrl:1
	v_rcp_f32_e32 v244, v244
	v_fmac_f32_dpp v218, v42, v154 row_ror:1 row_mask:0xf bank_mask:0xf bound_ctrl:1
	v_rcp_f32_e32 v245, v245
	v_fmac_f32_dpp v219, v43, v155 row_ror:1 row_mask:0xf bank_mask:0xf bound_ctrl:1
	v_rcp_f32_e32 v246, v246
	v_fmac_f32_dpp v220, v44, v156 row_ror:1 row_mask:0xf bank_mask:0xf bound_ctrl:1
	v_rcp_f32_e32 v247, v247
	v_fmac_f32_dpp v221, v45, v157 row_ror:1 row_mask:0xf bank_mask:0xf bound_ctrl:1
	v_rcp_f32_e32 v248, v248
	v_fmac_f32_dpp v222, v38, v158 row_ror:1 row_mask:0xf bank_mask:0xf bound_ctrl:1
	v_rcp_f32_e32 v249, v249
	v_fmac_f32_dpp v223, v39, v159 row_ror:1 row_mask:0xf bank_mask:0xf bound_ctrl:1
	v_pk_mul_f32 v[202:203], v[202:203], v[242:243]
	v_fmac_f32_dpp v224, v40, v160 row_ror:1 row_mask:0xf bank_mask:0xf bound_ctrl:1
	v_pk_mul_f32 v[204:205], v[204:205], v[244:245]
	v_fmac_f32_dpp v225, v41, v161 row_ror:1 row_mask:0xf bank_mask:0xf bound_ctrl:1
	v_pk_mul_f32 v[206:207], v[206:207], v[246:247]
	v_fmac_f32_dpp v218, v42, v182 row_ror:2 row_mask:0xf bank_mask:0xf bound_ctrl:1
	v_pk_mul_f32 v[226:227], v[226:227], v[248:249]
	v_fmac_f32_dpp v219, v43, v183 row_ror:2 row_mask:0xf bank_mask:0xf bound_ctrl:1
	v_pk_mul_f32 v[18:19], v[18:19], v[202:203]
	v_fmac_f32_dpp v220, v44, v184 row_ror:2 row_mask:0xf bank_mask:0xf bound_ctrl:1
	v_pk_mul_f32 v[20:21], v[20:21], v[204:205]
	v_fmac_f32_dpp v221, v45, v185 row_ror:2 row_mask:0xf bank_mask:0xf bound_ctrl:1
	v_pk_mul_f32 v[10:11], v[10:11], v[206:207]
	v_fmac_f32_dpp v222, v38, v190 row_ror:2 row_mask:0xf bank_mask:0xf bound_ctrl:1
	v_pk_mul_f32 v[12:13], v[12:13], v[226:227]
	v_fmac_f32_dpp v223, v39, v191 row_ror:2 row_mask:0xf bank_mask:0xf bound_ctrl:1
	v_cvt_pk_bf16_f32 v250, v18, v19
	v_fmac_f32_dpp v224, v40, v192 row_ror:2 row_mask:0xf bank_mask:0xf bound_ctrl:1
	v_cvt_pk_bf16_f32 v251, v20, v21
	v_fmac_f32_dpp v225, v41, v193 row_ror:2 row_mask:0xf bank_mask:0xf bound_ctrl:1
	v_cvt_pk_bf16_f32 v252, v10, v11
	v_cvt_pk_bf16_f32 v253, v12, v13
	global_store_dwordx4 v175, v[250:253], s[72:73]
	s_add_u32 s72, s84, 0xf2000
	s_addc_u32 s73, s85, 0
	v_pk_mul_f32 v[242:243], v[218:219], s[98:99]
	v_pk_mul_f32 v[244:245], v[220:221], s[98:99]
	v_pk_mul_f32 v[246:247], v[222:223], s[98:99]
	v_pk_mul_f32 v[248:249], v[224:225], s[98:99]
	v_exp_f32_e32 v242, v242
	v_exp_f32_e32 v243, v243
	v_exp_f32_e32 v244, v244
	v_exp_f32_e32 v245, v245
	v_exp_f32_e32 v246, v246
	v_exp_f32_e32 v247, v247
	v_exp_f32_e32 v248, v248
	v_exp_f32_e32 v249, v249
	v_pk_add_f32 v[242:243], v[242:243], s[92:93]
	v_pk_add_f32 v[244:245], v[244:245], s[92:93]
	v_pk_add_f32 v[246:247], v[246:247], s[92:93]
	v_pk_add_f32 v[248:249], v[248:249], s[92:93]
	v_rcp_f32_e32 v242, v242
	v_rcp_f32_e32 v243, v243
	v_rcp_f32_e32 v244, v244
	v_rcp_f32_e32 v245, v245
	v_rcp_f32_e32 v246, v246
	v_rcp_f32_e32 v247, v247
	v_rcp_f32_e32 v248, v248
	v_rcp_f32_e32 v249, v249
	v_pk_mul_f32 v[218:219], v[218:219], v[242:243]
	v_pk_mul_f32 v[220:221], v[220:221], v[244:245]
	v_pk_mul_f32 v[222:223], v[222:223], v[246:247]
	v_pk_mul_f32 v[224:225], v[224:225], v[248:249]
	v_pk_mul_f32 v[6:7], v[6:7], v[218:219]
	v_pk_mul_f32 v[8:9], v[8:9], v[220:221]
	v_pk_mul_f32 v[2:3], v[2:3], v[222:223]
	v_pk_mul_f32 v[4:5], v[4:5], v[224:225]
	v_cvt_pk_bf16_f32 v250, v6, v7
	v_cvt_pk_bf16_f32 v251, v8, v9
	v_cvt_pk_bf16_f32 v252, v2, v3
	v_cvt_pk_bf16_f32 v253, v4, v5
	global_store_dwordx4 v175, v[250:253], s[72:73]
	s_waitcnt lgkmcnt(0)
	s_barrier
	v_mov_b64_e32 v[194:195], 0
	v_mov_b64_e32 v[196:197], 0
	v_mov_b64_e32 v[198:199], 0
	v_mov_b64_e32 v[200:201], 0
	v_mov_b64_e32 v[210:211], 0
	v_mov_b64_e32 v[212:213], 0
	v_mov_b64_e32 v[214:215], 0
	v_mov_b64_e32 v[216:217], 0
	s_cmp_lt_i32 s15, 1
	s_cbranch_scc1 .Lepi_gp0
	s_and_saveexec_b64 s[70:71], s[40:41]
	ds_read_b128 v[194:197], v187
	ds_read_b128 v[198:201], v187 offset:16
	s_or_b64 exec, exec, s[70:71]
.Lepi_gp0:
	s_and_saveexec_b64 s[70:71], s[40:41]
	ds_read_b128 v[210:213], v187 offset:2048
	ds_read_b128 v[214:217], v187 offset:2064
	s_or_b64 exec, exec, s[70:71]
	s_waitcnt lgkmcnt(0)
	v_pk_mul_f32 v[202:203], v[150:151], v[78:79]
	v_pk_mul_f32 v[204:205], v[152:153], v[80:81]
	v_pk_mul_f32 v[206:207], v[58:59], v[82:83]
	v_pk_mul_f32 v[226:227], v[60:61], v[84:85]
	v_fmac_f32_dpp v202, v150, v26 row_shr:1 row_mask:0xf bank_mask:0xf bound_ctrl:1
	v_fmac_f32_dpp v203, v151, v27 row_shr:1 row_mask:0xf bank_mask:0xf bound_ctrl:1
	v_fmac_f32_dpp v204, v152, v28 row_shr:1 row_mask:0xf bank_mask:0xf bound_ctrl:1
	v_fmac_f32_dpp v205, v153, v29 row_shr:1 row_mask:0xf bank_mask:0xf bound_ctrl:1
	v_fmac_f32_dpp v206, v58, v74 row_shr:1 row_mask:0xf bank_mask:0xf bound_ctrl:1
	v_fmac_f32_dpp v207, v59, v75 row_shr:1 row_mask:0xf bank_mask:0xf bound_ctrl:1
	v_fmac_f32_dpp v226, v60, v76 row_shr:1 row_mask:0xf bank_mask:0xf bound_ctrl:1
	v_fmac_f32_dpp v227, v61, v77 row_shr:1 row_mask:0xf bank_mask:0xf bound_ctrl:1
	v_fmac_f32_dpp v202, v150, v14 row_shr:2 row_mask:0xf bank_mask:0xf bound_ctrl:1
	v_fmac_f32_dpp v203, v151, v15 row_shr:2 row_mask:0xf bank_mask:0xf bound_ctrl:1
	v_fmac_f32_dpp v204, v152, v16 row_shr:2 row_mask:0xf bank_mask:0xf bound_ctrl:1
	v_fmac_f32_dpp v205, v153, v17 row_shr:2 row_mask:0xf bank_mask:0xf bound_ctrl:1
	v_fmac_f32_dpp v206, v58, v22 row_shr:2 row_mask:0xf bank_mask:0xf bound_ctrl:1
	v_fmac_f32_dpp v207, v59, v23 row_shr:2 row_mask:0xf bank_mask:0xf bound_ctrl:1
	v_fmac_f32_dpp v226, v60, v24 row_shr:2 row_mask:0xf bank_mask:0xf bound_ctrl:1
	v_fmac_f32_dpp v227, v61, v25 row_shr:2 row_mask:0xf bank_mask:0xf bound_ctrl:1
	v_fmac_f32_dpp v202, v194, v154 row_ror:1 row_mask:0xf bank_mask:0xf bound_ctrl:1
	v_fmac_f32_dpp v203, v195, v155 row_ror:1 row_mask:0xf bank_mask:0xf bound_ctrl:1
	v_fmac_f32_dpp v204, v196, v156 row_ror:1 row_mask:0xf bank_mask:0xf bound_ctrl:1
	v_fmac_f32_dpp v205, v197, v157 row_ror:1 row_mask:0xf bank_mask:0xf bound_ctrl:1
	v_fmac_f32_dpp v206, v198, v158 row_ror:1 row_mask:0xf bank_mask:0xf bound_ctrl:1
	v_fmac_f32_dpp v207, v199, v159 row_ror:1 row_mask:0xf bank_mask:0xf bound_ctrl:1
	v_fmac_f32_dpp v226, v200, v160 row_ror:1 row_mask:0xf bank_mask:0xf bound_ctrl:1
	v_fmac_f32_dpp v227, v201, v161 row_ror:1 row_mask:0xf bank_mask:0xf bound_ctrl:1
	v_fmac_f32_dpp v202, v194, v182 row_ror:2 row_mask:0xf bank_mask:0xf bound_ctrl:1
	v_fmac_f32_dpp v203, v195, v183 row_ror:2 row_mask:0xf bank_mask:0xf bound_ctrl:1
	v_fmac_f32_dpp v204, v196, v184 row_ror:2 row_mask:0xf bank_mask:0xf bound_ctrl:1
	v_fmac_f32_dpp v205, v197, v185 row_ror:2 row_mask:0xf bank_mask:0xf bound_ctrl:1
	v_fmac_f32_dpp v206, v198, v190 row_ror:2 row_mask:0xf bank_mask:0xf bound_ctrl:1
	v_fmac_f32_dpp v207, v199, v191 row_ror:2 row_mask:0xf bank_mask:0xf bound_ctrl:1
	v_fmac_f32_dpp v226, v200, v192 row_ror:2 row_mask:0xf bank_mask:0xf bound_ctrl:1
	v_fmac_f32_dpp v227, v201, v193 row_ror:2 row_mask:0xf bank_mask:0xf bound_ctrl:1
	s_mov_b64 s[72:73], s[84:85]
	v_pk_mul_f32 v[218:219], v[70:71], v[78:79]
	v_pk_mul_f32 v[242:243], v[202:203], s[98:99]
	v_pk_mul_f32 v[220:221], v[72:73], v[80:81]
	v_pk_mul_f32 v[244:245], v[204:205], s[98:99]
	v_pk_mul_f32 v[222:223], v[66:67], v[82:83]
	v_pk_mul_f32 v[246:247], v[206:207], s[98:99]
	v_pk_mul_f32 v[224:225], v[68:69], v[84:85]
	v_pk_mul_f32 v[248:249], v[226:227], s[98:99]
	v_fmac_f32_dpp v218, v70, v26 row_shr:1 row_mask:0xf bank_mask:0xf bound_ctrl:1
	v_exp_f32_e32 v242, v242
	v_fmac_f32_dpp v219, v71, v27 row_shr:1 row_mask:0xf bank_mask:0xf bound_ctrl:1
	v_exp_f32_e32 v243, v243
	v_fmac_f32_dpp v220, v72, v28 row_shr:1 row_mask:0xf bank_mask:0xf bound_ctrl:1
	v_exp_f32_e32 v244, v244
	v_fmac_f32_dpp v221, v73, v29 row_shr:1 row_mask:0xf bank_mask:0xf bound_ctrl:1
	v_exp_f32_e32 v245, v245
	v_fmac_f32_dpp v222, v66, v74 row_shr:1 row_mask:0xf bank_mask:0xf bound_ctrl:1
	v_exp_f32_e32 v246, v246
	v_fmac_f32_dpp v223, v67, v75 row_shr:1 row_mask:0xf bank_mask:0xf bound_ctrl:1
	v_exp_f32_e32 v247, v247
	v_fmac_f32_dpp v224, v68, v76 row_shr:1 row_mask:0xf bank_mask:0xf bound_ctrl:1
	v_exp_f32_e32 v248, v248
	v_fmac_f32_dpp v225, v69, v77 row_shr:1 row_mask:0xf bank_mask:0xf bound_ctrl:1
	v_exp_f32_e32 v249, v249
	v_fmac_f32_dpp v218, v70, v14 row_shr:2 row_mask:0xf bank_mask:0xf bound_ctrl:1
	v_pk_add_f32 v[242:243], v[242:243], s[92:93]
	v_fmac_f32_dpp v219, v71, v15 row_shr:2 row_mask:0xf bank_mask:0xf bound_ctrl:1
	v_pk_add_f32 v[244:245], v[244:245], s[92:93]
	v_fmac_f32_dpp v220, v72, v16 row_shr:2 row_mask:0xf bank_mask:0xf bound_ctrl:1
	v_pk_add_f32 v[246:247], v[246:247], s[92:93]
	v_fmac_f32_dpp v221, v73, v17 row_shr:2 row_mask:0xf bank_mask:0xf bound_ctrl:1
	v_pk_add_f32 v[248:249], v[248:249], s[92:93]
	v_fmac_f32_dpp v222, v66, v22 row_shr:2 row_mask:0xf bank_mask:0xf bound_ctrl:1
	v_rcp_f32_e32 v242, v242
	v_fmac_f32_dpp v223, v67, v23 row_shr:2 row_mask:0xf bank_mask:0xf bound_ctrl:1
	v_rcp_f32_e32 v243, v243
	v_fmac_f32_dpp v224, v68, v24 row_shr:2 row_mask:0xf bank_mask:0xf bound_ctrl:1
	v_rcp_f32_e32 v244, v244
	v_fmac_f32_dpp v225, v69, v25 row_shr:2 row_mask:0xf bank_mask:0xf bound_ctrl:1
	v_rcp_f32_e32 v245, v245
	v_fmac_f32_dpp v218, v210, v154 row_ror:1 row_mask:0xf bank_mask:0xf bound_ctrl:1
	v_rcp_f32_e32 v246, v246
	v_fmac_f32_dpp v219, v211, v155 row_ror:1 row_mask:0xf bank_mask:0xf bound_ctrl:1
	v_rcp_f32_e32 v247, v247
	v_fmac_f32_dpp v220, v212, v156 row_ror:1 row_mask:0xf bank_mask:0xf bound_ctrl:1
	v_rcp_f32_e32 v248, v248
	v_fmac_f32_dpp v221, v213, v157 row_ror:1 row_mask:0xf bank_mask:0xf bound_ctrl:1
	v_rcp_f32_e32 v249, v249
	v_fmac_f32_dpp v222, v214, v158 row_ror:1 row_mask:0xf bank_mask:0xf bound_ctrl:1
	v_pk_mul_f32 v[202:203], v[202:203], v[242:243]
	v_fmac_f32_dpp v223, v215, v159 row_ror:1 row_mask:0xf bank_mask:0xf bound_ctrl:1
	v_pk_mul_f32 v[204:205], v[204:205], v[244:245]
	v_fmac_f32_dpp v224, v216, v160 row_ror:1 row_mask:0xf bank_mask:0xf bound_ctrl:1
	v_pk_mul_f32 v[206:207], v[206:207], v[246:247]
	v_fmac_f32_dpp v225, v217, v161 row_ror:1 row_mask:0xf bank_mask:0xf bound_ctrl:1
	v_pk_mul_f32 v[226:227], v[226:227], v[248:249]
	v_fmac_f32_dpp v218, v210, v182 row_ror:2 row_mask:0xf bank_mask:0xf bound_ctrl:1
	v_pk_mul_f32 v[142:143], v[142:143], v[202:203]
	v_fmac_f32_dpp v219, v211, v183 row_ror:2 row_mask:0xf bank_mask:0xf bound_ctrl:1
	v_pk_mul_f32 v[144:145], v[144:145], v[204:205]
	v_fmac_f32_dpp v220, v212, v184 row_ror:2 row_mask:0xf bank_mask:0xf bound_ctrl:1
	v_pk_mul_f32 v[138:139], v[138:139], v[206:207]
	v_fmac_f32_dpp v221, v213, v185 row_ror:2 row_mask:0xf bank_mask:0xf bound_ctrl:1
	v_pk_mul_f32 v[140:141], v[140:141], v[226:227]
	v_fmac_f32_dpp v222, v214, v190 row_ror:2 row_mask:0xf bank_mask:0xf bound_ctrl:1
	v_cvt_pk_bf16_f32 v250, v142, v143
	v_fmac_f32_dpp v223, v215, v191 row_ror:2 row_mask:0xf bank_mask:0xf bound_ctrl:1
	v_cvt_pk_bf16_f32 v251, v144, v145
	v_fmac_f32_dpp v224, v216, v192 row_ror:2 row_mask:0xf bank_mask:0xf bound_ctrl:1
	v_cvt_pk_bf16_f32 v252, v138, v139
	v_fmac_f32_dpp v225, v217, v193 row_ror:2 row_mask:0xf bank_mask:0xf bound_ctrl:1
	v_cvt_pk_bf16_f32 v253, v140, v141
	s_mov_b64 s[76:77], exec
	s_cmp_lg_u32 s15, 0
	s_cbranch_scc1 .Lepi_st00
	s_andn2_b64 s[76:77], exec, s[42:43]
.Lepi_st00:
	s_and_saveexec_b64 s[70:71], s[76:77]
	global_store_dwordx4 v175, v[250:253], s[72:73]
	s_or_b64 exec, exec, s[70:71]
	s_add_u32 s72, s84, 0xb0000
	s_addc_u32 s73, s85, 0
	v_pk_mul_f32 v[242:243], v[218:219], s[98:99]
	v_pk_mul_f32 v[244:245], v[220:221], s[98:99]
	v_pk_mul_f32 v[246:247], v[222:223], s[98:99]
	v_pk_mul_f32 v[248:249], v[224:225], s[98:99]
	v_exp_f32_e32 v242, v242
	v_exp_f32_e32 v243, v243
	v_exp_f32_e32 v244, v244
	v_exp_f32_e32 v245, v245
	v_exp_f32_e32 v246, v246
	v_exp_f32_e32 v247, v247
	v_exp_f32_e32 v248, v248
	v_exp_f32_e32 v249, v249
	v_pk_add_f32 v[242:243], v[242:243], s[92:93]
	v_pk_add_f32 v[244:245], v[244:245], s[92:93]
	v_pk_add_f32 v[246:247], v[246:247], s[92:93]
	v_pk_add_f32 v[248:249], v[248:249], s[92:93]
	v_rcp_f32_e32 v242, v242
	v_rcp_f32_e32 v243, v243
	v_rcp_f32_e32 v244, v244
	v_rcp_f32_e32 v245, v245
	v_rcp_f32_e32 v246, v246
	v_rcp_f32_e32 v247, v247
	v_rcp_f32_e32 v248, v248
	v_rcp_f32_e32 v249, v249
	v_pk_mul_f32 v[218:219], v[218:219], v[242:243]
	v_pk_mul_f32 v[220:221], v[220:221], v[244:245]
	v_pk_mul_f32 v[222:223], v[222:223], v[246:247]
	v_pk_mul_f32 v[224:225], v[224:225], v[248:249]
	v_pk_mul_f32 v[50:51], v[50:51], v[218:219]
	v_pk_mul_f32 v[52:53], v[52:53], v[220:221]
	v_pk_mul_f32 v[46:47], v[46:47], v[222:223]
	v_pk_mul_f32 v[48:49], v[48:49], v[224:225]
	v_cvt_pk_bf16_f32 v250, v50, v51
	v_cvt_pk_bf16_f32 v251, v52, v53
	v_cvt_pk_bf16_f32 v252, v46, v47
	v_cvt_pk_bf16_f32 v253, v48, v49
	global_store_dwordx4 v175, v[250:253], s[72:73]
	s_andn2_b64 vcc, exec, s[38:39]
	s_mov_b64 s[38:39], -1
	s_cbranch_vccnz .LBB0_239
	s_andn2_b64 vcc, exec, s[62:63]
	s_cbranch_vccnz .LBB0_238
	s_barrier
	s_branch .LBB0_238
